# GDN chain: one static s_setprio 1 for waves 4-7 for the duration of the chain (reset at chain end)
# speedup vs baseline: 1.0074x; 1.0074x over previous
; #define LAS __attribute__((address_space(3)))
; __device__ __forceinline__ void mixer_phase(const LAS Params* lp, int l, int rp, LAS unsigned char* lds, const XcdBarrier& xb) {
;     const bool ctxo = (l == 0);
;     const int nq = 64 + 256 + (ctxo ? 256 : 0);
;     unsigned* ctr = uni(lp->ctl) + 3584 + 64 * l + 16 * rp;
;     LAS int* slot = (LAS int*)(lds + PARAM_OFF + 512);
;     ...
;     for (int r = 0; r < SERIAL_MIX; ++r) { for (int it = blockIdx.x; it < 128; it += gridDim.x) chain_item<0>(lp, l, it, ctxo, lds); xcd_barrier(xb); }
;     ...
;     for (int it = blockIdx.x; it < 128; it += gridDim.x) chain_item<0>(lp, l, it, ctxo, lds);
;     ...
;     for (;;) {
;         __syncthreads();
;         if (threadIdx.x == 0) *slot = (int)atomicAdd(ctr, 1u);
.LBB0_1134:
	s_setprio 0
	v_readlane_b32 s0, v255, 25
	v_readlane_b32 s1, v255, 26
	s_and_b64 s[0:1], s[0:1], exec
	s_movk_i32 s0, 0x140
	s_cselect_b32 s27, 0x240, s0
	v_readlane_b32 s0, v255, 27
	s_lshl_b32 s6, s0, 6
	s_lshl_b32 s29, s0, 9
	s_lshl_b32 s90, s0, 3
	s_lshl_b64 s[0:1], s[6:7], 2
	s_add_u32 s0, s28, s0
	s_addc_u32 s1, s3, s1
	s_add_u32 s40, s0, 0x3800
	s_addc_u32 s41, s1, 0
	s_branch .LBB0_1167

; #define LAS __attribute__((address_space(3)))
; __device__ __forceinline__ int otid() { int t = threadIdx.x; asm volatile("" : "+v"(t)); return t; }
; __device__ __forceinline__ float softplusf(float v) { return fmaxf(v, 0.f) + log1pf(__expf(-fabsf(v))); }
; template <int MODE>
; __device__ NOINL void chain_item(const LAS Params* lp, int l, int item, bool ctx_out, LAS unsigned char* lds) {
;     ...
;     const int tid = otid(), w = tid >> 6, lane = tid & 63, fr = lane & 15, fq = lane >> 4;
;     LAS bf16_t* ST = (LAS bf16_t*)(lds + CH_WP + w * 6656);
;     LAS bf16_t* RP = (LAS bf16_t*)(lds + CH_WP + w * 6656 + 4352);
;     int b, h, dir;
;     if (MODE == 0) { b = item >> 3; h = (item >> 1) & 3; dir = item & 1; } else { b = item >> 2; h = ((item >> 1) & 1) * 2; dir = item & 1; }
;     constexpr int NDK = MODE == 0 ? 8 : 4;
;     constexpr int NKS = MODE == 0 ? 4 : 2;
;     const int hh = MODE == 0 ? 0 : (w >> 2);
;     const int dvrow = MODE == 0 ? 16 * w : 64 * hh + 16 * (w & 3);
;     const int kcol = MODE == 0 ? 0 : 64 * hh;
;     float lg = 0.f;
;     if (MODE == 1) { const float xl = p.ret_decay_logit[l * 8 + dir * 4 + h + hh]; lg = -softplusf(-xl); }
;     f32x4 Sacc[NDK];
; #pragma unroll
;     for (int i = 0; i < NDK; ++i) Sacc[i] = (f32x4){0.f, 0.f, 0.f, 0.f};
;     const int tk = tid >> 3, cg8 = tid & 7, pp = dir ? 63 - tk : tk;
;     const int ppz = (((pp >> 3) ^ cg8) << 3) | (pp & 7);
;     const int vkey = (dvrow >> 4) & 7;
;     const int lcol = MODE == 0 ? h * 128 + cg8 * 16 : 2048 + (h + (cg8 >> 2)) * 64 + (cg8 & 3) * 16;
;     const int lstep = MODE == 0 ? 512 : 256;
;     const int lrow = MODE == 0 ? cg8 * 16 : (cg8 >> 2) * 64 + (cg8 & 3) * 16;
;     float lgl = 0.f;
;     if (MODE == 1) lgl = -softplusf(-p.ret_decay_logit[l * 8 + dir * 4 + h + (cg8 >> 2)]);
;     u32x4 rq[2], rk[2], rv[2], rt; float rg = 0.f;
.LBB0_1140:
	s_or_b64 exec, exec, s[46:47]
	v_readfirstlane_b32 s22, v30
	s_nop 3
	s_cmpk_gt_u32 s22, 0xff
	s_cbranch_scc0 .Lmy_prio_gdn
	s_setprio 1
.Lmy_prio_gdn:
	v_ashrrev_i32_e32 v36, 6, v30
	v_mul_lo_u32 v3, v36, s30
	v_add_u32_e32 v37, s31, v3
	v_sub_u32_e32 v3, 63, v111
	v_cndmask_b32_e32 v40, v3, v111, vcc
	v_lshlrev_b32_e32 v3, 3, v29
	v_bitop3_b32 v3, v40, v3, s33 bitop3:0x6c
	v_and_or_b32 v41, v40, 7, v3
	v_mul_lo_u32 v3, v40, s35
	v_lshlrev_b32_e32 v2, 1, v2
	s_add_u32 s20, s20, s21
	v_and_b32_e32 v38, 15, v30
	v_bfe_u32 v39, v30, 4, 2
	v_lshlrev_b32_e32 v34, 4, v36
	v_add3_u32 v151, 0, v3, v2
	v_and_b32_e32 v3, 56, v32
	s_addc_u32 s21, s18, 0
	v_lshrrev_b32_e32 v35, 4, v30
	v_mul_lo_u32 v2, v111, s77
	v_lshlrev_b32_e32 v3, 1, v3
	v_readlane_b32 s22, v254, 63
	v_lshl_add_u64 v[108:109], v[32:33], 1, s[20:21]
	v_lshl_add_u32 v153, v40, 2, s34
	v_and_b32_e32 v32, -16, v111
	v_bfi_b32 v40, -16, v111, v30
	v_lshlrev_b32_e32 v154, 3, v39
	v_lshlrev_b32_e32 v155, 4, v39
	v_lshlrev_b32_e32 v39, 2, v39
	v_lshl_add_u32 v156, v30, 2, s34
	v_lshl_add_u64 v[114:115], v[30:31], 2, s[50:51]
	v_or_b32_e32 v31, v34, v38
	v_lshrrev_b32_e32 v30, 1, v30
	v_add3_u32 v152, s22, v2, v3
	v_lshl_add_u64 v[2:3], s[48:49], 0, v[0:1]
	v_lshlrev_b32_e32 v0, 5, v36
	v_add_u32_e32 v110, 0, v155
	v_or_b32_e32 v32, v39, v32
	s_lshl_b32 s18, s29, 11
	v_mul_lo_u32 v31, v31, s77
	v_and_b32_e32 v30, 8, v30
	v_lshl_add_u32 v33, v41, 1, 0
	v_mad_u64_u32 v[112:113], s[20:21], v40, s35, v[110:111]
	v_mul_u32_u24_e32 v40, 0x110, v38
	s_addk_i32 s18, 0xff00
	v_add3_u32 v41, 0, v31, v30
	v_mul_u32_u24_e32 v157, 0x90, v38
	v_and_or_b32 v0, v0, 32, v38
	v_or_b32_e32 v30, 1, v32
	v_or_b32_e32 v31, 2, v32
	v_or_b32_e32 v43, 3, v32
	v_add3_u32 v113, v37, v40, v154
	v_add3_u32 v158, v37, v157, v154
	s_add_u32 s19, s19, 0x200
	v_mul_u32_u24_e32 v37, 0x900, v29
	v_mad_u32_u24 v163, v29, s89, v33
	v_mul_u32_u24_e32 v29, 0x110, v0
	v_lshl_add_u32 v164, v0, 2, s34
	v_lshl_add_u32 v165, v0, 1, s86
	v_cmp_le_i32_e64 s[46:47], v0, v32
	v_cmp_le_i32_e64 s[48:49], v0, v30
	v_cmp_le_i32_e64 s[50:51], v0, v31
	v_cmp_le_i32_e64 s[52:53], v0, v43
	v_or_b32_e32 v0, 16, v0
	v_bfe_u32 v40, v35, 1, 1
	s_addc_u32 s5, s5, 0
	v_lshl_add_u32 v166, v32, 2, s34
	v_mul_lo_u32 v167, v32, s77
	v_lshl_add_u32 v174, v0, 2, s34
	v_cmp_le_i32_e64 s[54:55], v0, v32
	v_lshlrev_b32_e32 v32, 1, v0
	v_cmp_le_i32_e64 s[56:57], v0, v30
	v_cmp_le_i32_e64 s[58:59], v0, v31
	v_cmp_le_i32_e64 s[60:61], v0, v43
	v_mul_u32_u24_e32 v0, 0x88, v38
	v_and_b32_e32 v42, 7, v36
	v_lshl_add_u32 v179, v0, 1, v110
	v_bitop3_b32 v0, v40, v36, 7 bitop3:0x78
	s_and_b64 s[20:21], vcc, exec
	v_lshlrev_b32_e32 v45, 4, v0
	v_bitop3_b32 v0, v40, v42, 2 bitop3:0x36
	s_cselect_b32 s5, s5, s0
	s_cselect_b32 s0, s19, s1
	s_lshl_b32 s1, s4, 1
	v_lshlrev_b32_e32 v47, 4, v0
	v_bitop3_b32 v0, v40, v42, 4 bitop3:0x36
	s_add_u32 s0, s0, s1
	v_ashrrev_i32_e32 v35, 31, v34
	s_waitcnt vmcnt(7)
; #define LAS __attribute__((address_space(3)))
; __device__ __forceinline__ bf16_t f2bf(float f) { return (bf16_t)(pk2(f, f) & 0xFFFFu); }
; #define MFMA16(a, b, c) __builtin_amdgcn_mfma_f32_16x16x32_bf16((a), (b), (c), 0, 0, 0)
; template <int MODE>
; __device__ NOINL void chain_item(const LAS Params* lp, int l, int item, bool ctx_out, LAS unsigned char* lds) {
;     ...
;     f32x4 Sacc[NDK];
; #pragma unroll
;     for (int i = 0; i < NDK; ++i) Sacc[i] = (f32x4){0.f, 0.f, 0.f, 0.f};
;     const int tk = tid >> 3, cg8 = tid & 7, pp = dir ? 63 - tk : tk;
;     const int ppz = (((pp >> 3) ^ cg8) << 3) | (pp & 7);
;     ...
;             bf16_t* ob; int ldo;
;             if (MODE == 0) { if (dir == 0) { ob = p.hbuf + 256 + h * 128 + 16 * w; ldo = 1024; } else { ob = p.hyproj + h * 128 + 16 * w; ldo = 768; } }
;             else { if (dir == 0) { ob = p.hbuf + 768 + (h + hh) * 64 + 16 * (w & 3); ldo = 1024; } else { ob = p.hyproj + 512 + (h + hh) * 64 + 16 * (w & 3); ldo = 768; } }
; #pragma unroll
;             for (int ct = 0; ct < 4; ++ct) {
;                 f32x4 acc = {0.f, 0.f, 0.f, 0.f};
; #pragma unroll
;                 for (int ks = 0; ks < 2; ++ks) { const bf16x8 A = *(const LAS bf16x8*)(AT + hh * 4608 + (16 * ct + fr) * 72 + ks * 32 + fq * 8); acc = MFMA16(A, Bv[ks], acc); }
;                 gbf16* og = (gbf16*)ob + (size_t)row0 * ldo + fr;
; #pragma unroll
;                 for (int j = 0; j < 4; ++j) { const int c = 16 * ct + 4 * fq + j, tok = dir ? 63 - c : c; og[tok * ldo] = f2bf(eg[ct][j] * qs[ct][j] + acc[j]); }
	v_lshlrev_b32_e32 v49, 4, v0
	v_bitop3_b32 v0, v40, v42, 6 bitop3:0x36
	s_addc_u32 s1, s5, 0
	v_lshl_add_u32 v168, v30, 2, s34
	v_lshl_add_u32 v170, v31, 2, s34
	v_lshlrev_b32_e32 v51, 4, v0
	v_lshl_add_u64 v[30:31], v[34:35], 1, s[0:1]
	v_lshlrev_b32_e32 v0, 1, v38
	v_add_u32_e32 v169, 0x90, v167
	v_add_u32_e32 v171, 0x120, v167
	v_add_u32_e32 v173, 0x1b0, v167
	v_lshl_add_u64 v[116:117], v[30:31], 0, v[0:1]
	v_or_b32_e32 v30, 1, v39
	v_xor_b32_e32 v31, 62, v39
	v_add3_u32 v175, s86, v167, v32
	v_add3_u32 v176, s86, v169, v32
	v_add3_u32 v177, s86, v171, v32
	v_add3_u32 v178, s86, v173, v32
	s_and_b64 s[0:1], vcc, exec
	v_cndmask_b32_e32 v30, v31, v30, vcc
	v_or_b32_e32 v31, 2, v39
	v_xor_b32_e32 v32, 61, v39
	s_cselect_b32 s19, s8, 0x300
	v_cndmask_b32_e32 v31, v32, v31, vcc
	v_mul_u32_u24_e32 v32, s19, v31
	v_or_b32_e32 v31, 3, v39
	v_xor_b32_e32 v34, 60, v39
	v_cndmask_b32_e32 v31, v34, v31, vcc
	v_mul_u32_u24_e32 v34, s19, v31
	v_or_b32_e32 v31, 16, v39
	v_xor_b32_e32 v35, 47, v39
	v_cndmask_b32_e32 v31, v35, v31, vcc
	v_mul_u32_u24_e32 v36, s19, v31
	v_or_b32_e32 v31, 17, v39
	v_xor_b32_e32 v35, 46, v39
	v_cndmask_b32_e32 v31, v35, v31, vcc
	v_mad_u32_u24 v161, v38, s77, 0
	v_lshl_add_u32 v172, v43, 2, s34
	v_or_b32_e32 v43, 16, v38
	v_mul_u32_u24_e32 v38, s19, v31
	v_or_b32_e32 v31, 18, v39
	v_xor_b32_e32 v35, 45, v39
	v_cndmask_b32_e32 v31, v35, v31, vcc
	v_mul_u32_u24_e32 v40, s19, v31
	v_or_b32_e32 v31, 19, v39
	v_xor_b32_e32 v35, 44, v39
	v_cndmask_b32_e32 v31, v35, v31, vcc
	v_mul_u32_u24_e32 v42, s19, v31
	v_or_b32_e32 v31, 32, v39
	v_xor_b32_e32 v35, 31, v39
	v_cndmask_b32_e32 v31, v35, v31, vcc
	v_mul_u32_u24_e32 v44, s19, v31
	v_or_b32_e32 v31, 33, v39
	v_xor_b32_e32 v35, 30, v39
	v_cndmask_b32_e32 v31, v35, v31, vcc
	v_mul_u32_u24_e32 v46, s19, v31
	v_or_b32_e32 v31, 34, v39
	v_xor_b32_e32 v35, 29, v39
	v_cndmask_b32_e32 v31, v35, v31, vcc
	v_mul_u32_u24_e32 v48, s19, v31
	v_or_b32_e32 v31, 35, v39
	v_xor_b32_e32 v35, 28, v39
	v_cndmask_b32_e32 v31, v35, v31, vcc
	v_mul_u32_u24_e32 v50, s19, v31
	v_or_b32_e32 v31, 48, v39
	v_xor_b32_e32 v35, 15, v39
	v_cndmask_b32_e32 v31, v35, v31, vcc
	v_mul_u32_u24_e32 v52, s19, v31
	v_or_b32_e32 v31, 49, v39
	v_xor_b32_e32 v35, 14, v39
	v_cndmask_b32_e32 v31, v35, v31, vcc
	v_mul_u32_u24_e32 v54, s19, v31
	v_or_b32_e32 v31, 50, v39
	v_xor_b32_e32 v35, 13, v39
	v_cndmask_b32_e32 v31, v35, v31, vcc
	v_xor_b32_e32 v0, 63, v39
	v_mul_u32_u24_e32 v56, s19, v31
	v_or_b32_e32 v31, 51, v39
	v_xor_b32_e32 v35, 12, v39
	v_cndmask_b32_e32 v0, v0, v39, vcc
	v_cndmask_b32_e32 v31, v35, v31, vcc
	v_mad_u32_u24 v181, v43, s77, 0
	v_xor_b32_e32 v162, 48, v155
	v_mul_u32_u24_e32 v0, s19, v0
	v_mul_u32_u24_e32 v30, s19, v30
	v_mul_u32_u24_e32 v58, s19, v31
	v_add_u32_e32 v31, 0x900, v181
	v_xor_b32_e32 v183, 32, v155
	v_add_u32_e32 v35, 0x1200, v181
	v_add_u32_e32 v159, s22, v155
	v_add_u32_e32 v160, s86, v155
	v_mul_u32_u24_e32 v180, 0x90, v43
	v_xor_b32_e32 v182, 16, v155
	s_mov_b32 s1, 0
	s_mov_b32 s4, -1
	v_add_u32_e32 v185, v33, v37
	v_add_u32_e32 v186, v41, v45
	v_add_u32_e32 v187, v41, v47
	v_add_u32_e32 v188, v41, v49
	v_add_u32_e32 v189, v41, v51
	v_lshlrev_b32_e32 v0, 1, v0
	v_lshlrev_b32_e32 v118, 1, v30
	v_lshlrev_b32_e32 v120, 1, v32
	v_lshlrev_b32_e32 v122, 1, v34
	v_lshlrev_b32_e32 v124, 1, v36
	v_lshlrev_b32_e32 v126, 1, v38
	v_lshlrev_b32_e32 v128, 1, v40
	v_lshlrev_b32_e32 v130, 1, v42
	v_lshlrev_b32_e32 v132, 1, v44
	v_lshlrev_b32_e32 v134, 1, v46
	v_lshlrev_b32_e32 v136, 1, v48
	v_lshlrev_b32_e32 v138, 1, v50
	v_lshlrev_b32_e32 v140, 1, v52
	v_lshlrev_b32_e32 v142, 1, v54
	v_lshlrev_b32_e32 v144, 1, v56
	v_lshlrev_b32_e32 v146, 1, v58
	v_add_u32_e32 v190, v31, v183
	v_add_u32_e32 v191, v35, v162
	v_add_u32_e32 v192, v110, v29
	v_mov_b32_e32 v29, v28
	v_mov_b32_e32 v30, v28
	v_mov_b32_e32 v31, v28
	v_mov_b32_e32 v40, v28
	v_mov_b32_e32 v41, v28
	v_mov_b32_e32 v42, v28
	v_mov_b32_e32 v43, v28
	v_mov_b32_e32 v32, v28
	v_mov_b32_e32 v33, v28
	v_mov_b32_e32 v34, v28
	v_mov_b32_e32 v35, v28
	v_mov_b32_e32 v36, v28
	v_mov_b32_e32 v37, v28
	v_mov_b32_e32 v38, v28
	v_mov_b32_e32 v39, v28
	v_mov_b32_e32 v56, v28
	v_mov_b32_e32 v57, v28
	v_mov_b32_e32 v58, v28
	v_mov_b32_e32 v59, v28
	v_mov_b32_e32 v52, v28
	v_mov_b32_e32 v53, v28
	v_mov_b32_e32 v54, v28
	v_mov_b32_e32 v55, v28
	v_mov_b32_e32 v44, v28
	v_mov_b32_e32 v45, v28
	v_mov_b32_e32 v46, v28
	v_mov_b32_e32 v47, v28
	v_mov_b32_e32 v48, v28
	v_mov_b32_e32 v49, v28
	v_mov_b32_e32 v50, v28
	v_mov_b32_e32 v51, v28
	s_branch .LBB0_1142
